# prologue/epilogue de-serialisation: peerq sub-key tile fetched by 8 loads issued together two K-steps before the epilogue, instead of a load-wait-ds_write ladder of 8 round trips per tile
# speedup vs baseline: 1.0076x; 1.0076x over previous
; DI int crow(int r, int h) { return (r & 3) + 8 * (r >> 2) + 4 * h; }
; #define D_COMPUTE(BUF) { D_MMA1(BUF, 0) D_MMA1(BUF, 1) D_MMA1(BUF, 2) D_MMA1(BUF, 3) }
; template <bool RESCALE, bool SWAP>
; DI void gemm_mainloop_glds(const bf16_t* __restrict__ A, const bf16_t* __restrict__ Bt, int m0, int n0, char* lds,
;                            f32x16 (&acc)[2][2], const float* ratio_lds) {
;     ...
;   for (int kt = 0; kt < NK; kt += 2) {
;     D_ISSUE(1, kt + 1);
;     if (RESCALE) {
;       if (kt == NK / 2) {
;         if (SWAP) {
;           const float sc0_ = ratio_lds[64 * wm + l31], sc1_ = ratio_lds[64 * wm + 32 + l31];
; #pragma unroll
;           for (int r = 0; r < 16; ++r) { c00[r] *= sc0_; c10[r] *= sc0_; c01[r] *= sc1_; c11[r] *= sc1_; }
;         } else {
; #pragma unroll
;           for (int r = 0; r < 16; ++r) {
;             float sc0_ = ratio_lds[64 * wm + crow(r, h)], sc1_ = ratio_lds[64 * wm + 32 + crow(r, h)];
;             c00[r] *= sc0_; c01[r] *= sc0_; c10[r] *= sc1_; c11[r] *= sc1_;
;           }
;         }
;       }
;     }
;     D_COMPUTE(0);
;     __syncthreads();
;     if (kt + 2 < NK) D_ISSUE(0, kt + 2);
;     D_COMPUTE(1);
;     __syncthreads();
;   }
.Lgm_pq_loop:
	ds_read_b128 v[184:187], v109
	ds_read_b128 v[188:191], v109 offset:4096
	ds_read_b128 v[192:195], v113 offset:16384
	ds_read_b128 v[196:199], v113 offset:20480
	ds_read_b128 v[200:203], v110
	ds_read_b128 v[204:207], v110 offset:4096
	ds_read_b128 v[208:211], v115 offset:16384
	ds_read_b128 v[212:215], v115 offset:20480
	ds_read_b128 v[216:219], v111
	ds_read_b128 v[220:223], v111 offset:4096
	ds_read_b128 v[224:227], v116 offset:16384
	ds_read_b128 v[228:231], v116 offset:20480
	ds_read_b128 v[232:235], v112
	ds_read_b128 v[236:239], v112 offset:4096
	ds_read_b128 v[240:243], v117 offset:16384
	ds_read_b128 v[244:247], v117 offset:20480
	s_waitcnt lgkmcnt(0)
	s_barrier
	s_mov_b32 m0, s19
	v_lshl_add_u64 v[86:87], v[130:131], 0, v[86:87]
	global_load_lds_dwordx4 v[86:87], off
	s_add_u32 m0, s19, 0x4000
	v_lshl_add_u64 v[88:89], v[130:131], 0, v[88:89]
	global_load_lds_dwordx4 v[88:89], off
	s_add_u32 m0, s19, 0x1000
	v_lshl_add_u64 v[90:91], v[130:131], 0, v[90:91]
	global_load_lds_dwordx4 v[90:91], off
	s_add_u32 m0, s19, 0x5000
	v_lshl_add_u64 v[92:93], v[130:131], 0, v[92:93]
	global_load_lds_dwordx4 v[92:93], off
	s_add_u32 m0, s19, 0x2000
	v_lshl_add_u64 v[136:137], v[130:131], 0, v[136:137]
	global_load_lds_dwordx4 v[136:137], off
	s_add_u32 m0, s19, 0x6000
	v_lshl_add_u64 v[138:139], v[130:131], 0, v[138:139]
	global_load_lds_dwordx4 v[138:139], off
	s_add_u32 m0, s19, 0x3000
	v_lshl_add_u64 v[140:141], v[130:131], 0, v[140:141]
	global_load_lds_dwordx4 v[140:141], off
	s_add_u32 m0, s19, 0x7000
	v_lshl_add_u64 v[142:143], v[130:131], 0, v[142:143]
	global_load_lds_dwordx4 v[142:143], off
	v_mfma_f32_32x32x16_bf16 v[0:15], v[192:195], v[184:187], v[0:15]
	v_mfma_f32_32x32x16_bf16 v[16:31], v[192:195], v[188:191], v[16:31]
	v_mfma_f32_32x32x16_bf16 v[32:47], v[196:199], v[184:187], v[32:47]
	v_mfma_f32_32x32x16_bf16 v[48:63], v[196:199], v[188:191], v[48:63]
	v_mfma_f32_32x32x16_bf16 v[0:15], v[208:211], v[200:203], v[0:15]
	v_mfma_f32_32x32x16_bf16 v[16:31], v[208:211], v[204:207], v[16:31]
	v_mfma_f32_32x32x16_bf16 v[32:47], v[212:215], v[200:203], v[32:47]
	v_mfma_f32_32x32x16_bf16 v[48:63], v[212:215], v[204:207], v[48:63]
	v_mfma_f32_32x32x16_bf16 v[0:15], v[224:227], v[216:219], v[0:15]
	v_mfma_f32_32x32x16_bf16 v[16:31], v[224:227], v[220:223], v[16:31]
	v_mfma_f32_32x32x16_bf16 v[32:47], v[228:231], v[216:219], v[32:47]
	v_mfma_f32_32x32x16_bf16 v[48:63], v[228:231], v[220:223], v[48:63]
	v_mfma_f32_32x32x16_bf16 v[0:15], v[240:243], v[232:235], v[0:15]
	v_mfma_f32_32x32x16_bf16 v[16:31], v[240:243], v[236:239], v[16:31]
	v_mfma_f32_32x32x16_bf16 v[32:47], v[244:247], v[232:235], v[32:47]
	v_mfma_f32_32x32x16_bf16 v[48:63], v[244:247], v[236:239], v[48:63]
	s_waitcnt vmcnt(8)
	s_barrier
	ds_read_b128 v[184:187], v109 offset:32768
	ds_read_b128 v[188:191], v109 offset:36864
	ds_read_b128 v[192:195], v113 offset:49152
	ds_read_b128 v[196:199], v113 offset:53248
	ds_read_b128 v[200:203], v110 offset:32768
	ds_read_b128 v[204:207], v110 offset:36864
	ds_read_b128 v[208:211], v115 offset:49152
	ds_read_b128 v[212:215], v115 offset:53248
	ds_read_b128 v[216:219], v111 offset:32768
	ds_read_b128 v[220:223], v111 offset:36864
	ds_read_b128 v[224:227], v116 offset:49152
	ds_read_b128 v[228:231], v116 offset:53248
	ds_read_b128 v[232:235], v112 offset:32768
	ds_read_b128 v[236:239], v112 offset:36864
	ds_read_b128 v[240:243], v117 offset:49152
	ds_read_b128 v[244:247], v117 offset:53248
	s_waitcnt lgkmcnt(0)
	s_barrier
	s_add_u32 m0, s19, 0x8000
	v_lshl_add_u64 v[86:87], v[130:131], 0, v[86:87]
	global_load_lds_dwordx4 v[86:87], off
	s_add_u32 m0, s19, 0xc000
	v_lshl_add_u64 v[88:89], v[130:131], 0, v[88:89]
	global_load_lds_dwordx4 v[88:89], off
	s_add_u32 m0, s19, 0x9000
	v_lshl_add_u64 v[90:91], v[130:131], 0, v[90:91]
	global_load_lds_dwordx4 v[90:91], off
	s_add_u32 m0, s19, 0xd000
	v_lshl_add_u64 v[92:93], v[130:131], 0, v[92:93]
	global_load_lds_dwordx4 v[92:93], off
	s_add_u32 m0, s19, 0xa000
	v_lshl_add_u64 v[136:137], v[130:131], 0, v[136:137]
	global_load_lds_dwordx4 v[136:137], off
	s_add_u32 m0, s19, 0xe000
	v_lshl_add_u64 v[138:139], v[130:131], 0, v[138:139]
	global_load_lds_dwordx4 v[138:139], off
	s_add_u32 m0, s19, 0xb000
	v_lshl_add_u64 v[140:141], v[130:131], 0, v[140:141]
	global_load_lds_dwordx4 v[140:141], off
	s_add_u32 m0, s19, 0xf000
	v_lshl_add_u64 v[142:143], v[130:131], 0, v[142:143]
	global_load_lds_dwordx4 v[142:143], off
	v_mfma_f32_32x32x16_bf16 v[0:15], v[192:195], v[184:187], v[0:15]
	v_mfma_f32_32x32x16_bf16 v[16:31], v[192:195], v[188:191], v[16:31]
	v_mfma_f32_32x32x16_bf16 v[32:47], v[196:199], v[184:187], v[32:47]
	v_mfma_f32_32x32x16_bf16 v[48:63], v[196:199], v[188:191], v[48:63]
	v_mfma_f32_32x32x16_bf16 v[0:15], v[208:211], v[200:203], v[0:15]
	v_mfma_f32_32x32x16_bf16 v[16:31], v[208:211], v[204:207], v[16:31]
	v_mfma_f32_32x32x16_bf16 v[32:47], v[212:215], v[200:203], v[32:47]
	v_mfma_f32_32x32x16_bf16 v[48:63], v[212:215], v[204:207], v[48:63]
	v_mfma_f32_32x32x16_bf16 v[0:15], v[224:227], v[216:219], v[0:15]
	v_mfma_f32_32x32x16_bf16 v[16:31], v[224:227], v[220:223], v[16:31]
	v_mfma_f32_32x32x16_bf16 v[32:47], v[228:231], v[216:219], v[32:47]
	v_mfma_f32_32x32x16_bf16 v[48:63], v[228:231], v[220:223], v[48:63]
	v_mfma_f32_32x32x16_bf16 v[0:15], v[240:243], v[232:235], v[0:15]
	v_mfma_f32_32x32x16_bf16 v[16:31], v[240:243], v[236:239], v[16:31]
	v_mfma_f32_32x32x16_bf16 v[32:47], v[244:247], v[232:235], v[32:47]
	v_mfma_f32_32x32x16_bf16 v[48:63], v[244:247], v[236:239], v[48:63]
	s_waitcnt vmcnt(8)
	s_barrier
	s_add_i32 s1, s1, 2
	s_cmp_lt_u32 s1, 14
	s_cbranch_scc1 .Lgm_pq_loop
; DI int crow(int r, int h) { return (r & 3) + 8 * (r >> 2) + 4 * h; }
; #define D_COMPUTE(BUF) { D_MMA1(BUF, 0) D_MMA1(BUF, 1) D_MMA1(BUF, 2) D_MMA1(BUF, 3) }
; template <bool RESCALE, bool SWAP>
; DI void gemm_mainloop_glds(const bf16_t* __restrict__ A, const bf16_t* __restrict__ Bt, int m0, int n0, char* lds,
;                            f32x16 (&acc)[2][2], const float* ratio_lds) {
;     ...
;   for (int kt = 0; kt < NK; kt += 2) {
;     D_ISSUE(1, kt + 1);
;     if (RESCALE) {
;       if (kt == NK / 2) {
;         if (SWAP) {
;           const float sc0_ = ratio_lds[64 * wm + l31], sc1_ = ratio_lds[64 * wm + 32 + l31];
; #pragma unroll
;           for (int r = 0; r < 16; ++r) { c00[r] *= sc0_; c10[r] *= sc0_; c01[r] *= sc1_; c11[r] *= sc1_; }
;         } else {
; #pragma unroll
;           for (int r = 0; r < 16; ++r) {
;             float sc0_ = ratio_lds[64 * wm + crow(r, h)], sc1_ = ratio_lds[64 * wm + 32 + crow(r, h)];
;             c00[r] *= sc0_; c01[r] *= sc0_; c10[r] *= sc1_; c11[r] *= sc1_;
;           }
;         }
;       }
;     }
;     D_COMPUTE(0);
;     __syncthreads();
;     if (kt + 2 < NK) D_ISSUE(0, kt + 2);
;     D_COMPUTE(1);
;     __syncthreads();
;   }
;   acc[0][0] = c00; acc[0][1] = c01; acc[1][0] = c10; acc[1][1] = c11;
; __device__ void phase_peerq(const Params& p, int bid, int nb, char* lds, const TileMap& tm) {
;     ...
;     for (int i = 0; i < 8; ++i) {
;       int c = tid + 256 * i, row = c >> 4, c16 = c & 15;
;       *(uint4*)(ks + row * LDS_ST + c16 * 8) = *(const uint4*)(skb + ((size_t)hp * 128 + row) * 128 + c16 * 8);
;     }
	s_ashr_i32 s19, s18, 31
	s_lshl_b64 s[0:1], s[18:19], 15
	v_lshl_add_u64 v[132:133], v[66:67], 0, s[0:1]
	v_lshl_add_u64 v[130:131], v[132:133], 0, v[68:69]
	global_load_dwordx4 v[86:89], v[130:131], off
	v_lshl_add_u64 v[130:131], v[132:133], 0, v[70:71]
	global_load_dwordx4 v[90:93], v[130:131], off
	v_lshl_add_u64 v[130:131], v[132:133], 0, v[72:73]
	global_load_dwordx4 v[136:139], v[130:131], off
	v_lshl_add_u64 v[130:131], v[132:133], 0, v[74:75]
	global_load_dwordx4 v[140:143], v[130:131], off
	v_lshl_add_u64 v[130:131], v[132:133], 0, v[76:77]
	global_load_dwordx4 v[248:251], v[130:131], off
	v_lshl_add_u64 v[130:131], v[132:133], 0, v[78:79]
	global_load_dwordx4 v[252:255], v[130:131], off
	v_lshl_add_u64 v[130:131], v[132:133], 0, v[80:81]
	global_load_dwordx4 v[120:123], v[130:131], off
	v_lshl_add_u64 v[130:131], v[132:133], 0, v[82:83]
	global_load_dwordx4 v[126:129], v[130:131], off
	ds_read_b128 v[184:187], v109
	ds_read_b128 v[188:191], v109 offset:4096
	ds_read_b128 v[192:195], v113 offset:16384
	ds_read_b128 v[196:199], v113 offset:20480
	ds_read_b128 v[200:203], v110
	ds_read_b128 v[204:207], v110 offset:4096
	ds_read_b128 v[208:211], v115 offset:16384
	ds_read_b128 v[212:215], v115 offset:20480
	ds_read_b128 v[216:219], v111
	ds_read_b128 v[220:223], v111 offset:4096
	ds_read_b128 v[224:227], v116 offset:16384
	ds_read_b128 v[228:231], v116 offset:20480
	ds_read_b128 v[232:235], v112
	ds_read_b128 v[236:239], v112 offset:4096
	ds_read_b128 v[240:243], v117 offset:16384
	ds_read_b128 v[244:247], v117 offset:20480
	s_waitcnt lgkmcnt(0)
	v_mfma_f32_32x32x16_bf16 v[0:15], v[192:195], v[184:187], v[0:15]
	v_mfma_f32_32x32x16_bf16 v[16:31], v[192:195], v[188:191], v[16:31]
	v_mfma_f32_32x32x16_bf16 v[32:47], v[196:199], v[184:187], v[32:47]
	v_mfma_f32_32x32x16_bf16 v[48:63], v[196:199], v[188:191], v[48:63]
	v_mfma_f32_32x32x16_bf16 v[0:15], v[208:211], v[200:203], v[0:15]
	v_mfma_f32_32x32x16_bf16 v[16:31], v[208:211], v[204:207], v[16:31]
	v_mfma_f32_32x32x16_bf16 v[32:47], v[212:215], v[200:203], v[32:47]
	v_mfma_f32_32x32x16_bf16 v[48:63], v[212:215], v[204:207], v[48:63]
	v_mfma_f32_32x32x16_bf16 v[0:15], v[224:227], v[216:219], v[0:15]
	v_mfma_f32_32x32x16_bf16 v[16:31], v[224:227], v[220:223], v[16:31]
	v_mfma_f32_32x32x16_bf16 v[32:47], v[228:231], v[216:219], v[32:47]
	v_mfma_f32_32x32x16_bf16 v[48:63], v[228:231], v[220:223], v[48:63]
	v_mfma_f32_32x32x16_bf16 v[0:15], v[240:243], v[232:235], v[0:15]
	v_mfma_f32_32x32x16_bf16 v[16:31], v[240:243], v[236:239], v[16:31]
	v_mfma_f32_32x32x16_bf16 v[32:47], v[244:247], v[232:235], v[32:47]
	v_mfma_f32_32x32x16_bf16 v[48:63], v[244:247], v[236:239], v[48:63]
	s_waitcnt vmcnt(8)
	s_barrier
	ds_read_b128 v[184:187], v109 offset:32768
	ds_read_b128 v[188:191], v109 offset:36864
	ds_read_b128 v[192:195], v113 offset:49152
	ds_read_b128 v[196:199], v113 offset:53248
	ds_read_b128 v[200:203], v110 offset:32768
	ds_read_b128 v[204:207], v110 offset:36864
	ds_read_b128 v[208:211], v115 offset:49152
	ds_read_b128 v[212:215], v115 offset:53248
	ds_read_b128 v[216:219], v111 offset:32768
	ds_read_b128 v[220:223], v111 offset:36864
	ds_read_b128 v[224:227], v116 offset:49152
	ds_read_b128 v[228:231], v116 offset:53248
	ds_read_b128 v[232:235], v112 offset:32768
	ds_read_b128 v[236:239], v112 offset:36864
	ds_read_b128 v[240:243], v117 offset:49152
	ds_read_b128 v[244:247], v117 offset:53248
	s_waitcnt lgkmcnt(0)
	s_barrier
	v_mfma_f32_32x32x16_bf16 v[0:15], v[192:195], v[184:187], v[0:15]
	v_mfma_f32_32x32x16_bf16 v[16:31], v[192:195], v[188:191], v[16:31]
	v_mfma_f32_32x32x16_bf16 v[32:47], v[196:199], v[184:187], v[32:47]
	v_mfma_f32_32x32x16_bf16 v[48:63], v[196:199], v[188:191], v[48:63]
	v_mfma_f32_32x32x16_bf16 v[0:15], v[208:211], v[200:203], v[0:15]
	v_mfma_f32_32x32x16_bf16 v[16:31], v[208:211], v[204:207], v[16:31]
	v_mfma_f32_32x32x16_bf16 v[32:47], v[212:215], v[200:203], v[32:47]
	v_mfma_f32_32x32x16_bf16 v[48:63], v[212:215], v[204:207], v[48:63]
	v_mfma_f32_32x32x16_bf16 v[0:15], v[224:227], v[216:219], v[0:15]
	v_mfma_f32_32x32x16_bf16 v[16:31], v[224:227], v[220:223], v[16:31]
	v_mfma_f32_32x32x16_bf16 v[32:47], v[228:231], v[216:219], v[32:47]
	v_mfma_f32_32x32x16_bf16 v[48:63], v[228:231], v[220:223], v[48:63]
	v_mfma_f32_32x32x16_bf16 v[0:15], v[240:243], v[232:235], v[0:15]
	v_mfma_f32_32x32x16_bf16 v[16:31], v[240:243], v[236:239], v[16:31]
	v_mfma_f32_32x32x16_bf16 v[32:47], v[244:247], v[232:235], v[32:47]
	v_mfma_f32_32x32x16_bf16 v[48:63], v[244:247], v[236:239], v[48:63]
	s_nop 7
	s_nop 7
; __device__ void phase_peerq(const Params& p, int bid, int nb, char* lds, const TileMap& tm) {
;     ...
; #pragma unroll
;     for (int j = 0; j < 2; ++j)
; #pragma unroll
;       for (int i = 0; i < 2; ++i)
; #pragma unroll
;         for (int g = 0; g < 4; ++g) {
;           const f32x16& a = acc[j][i];
;           *(uint2*)(qs + (64 * wm + 32 * i + l31) * LDS_ST + 64 * wn + 32 * j + 8 * g + 4 * h) =
;               make_uint2(pack2(a[4 * g], a[4 * g + 1]), pack2(a[4 * g + 2], a[4 * g + 3]));
;         }
; #pragma unroll
;     for (int i = 0; i < 8; ++i) {
;       int c = tid + 256 * i, row = c >> 4, c16 = c & 15;
;       *(uint4*)(ks + row * LDS_ST + c16 * 8) = *(const uint4*)(skb + ((size_t)hp * 128 + row) * 128 + c16 * 8);
;     }
;     __syncthreads();
.LBB0_453:
	s_nop 4
	v_cvt_pk_bf16_f32 v0, v0, v1
	v_cvt_pk_bf16_f32 v1, v2, v3
	v_cvt_pk_bf16_f32 v2, v4, v5
	v_cvt_pk_bf16_f32 v3, v6, v7
	ds_write2_b64 v85, v[0:1], v[2:3] offset1:2
	v_cvt_pk_bf16_f32 v0, v8, v9
	v_cvt_pk_bf16_f32 v1, v10, v11
	v_cvt_pk_bf16_f32 v2, v12, v13
	v_cvt_pk_bf16_f32 v3, v14, v15
	ds_write2_b64 v85, v[0:1], v[2:3] offset0:4 offset1:6
	v_cvt_pk_bf16_f32 v0, v16, v17
	v_cvt_pk_bf16_f32 v1, v18, v19
	v_cvt_pk_bf16_f32 v2, v20, v21
	v_cvt_pk_bf16_f32 v3, v22, v23
	v_add_u32_e32 v4, 0x2000, v85
	ds_write2_b64 v4, v[0:1], v[2:3] offset0:64 offset1:66
	v_cvt_pk_bf16_f32 v0, v24, v25
	v_cvt_pk_bf16_f32 v1, v26, v27
	v_cvt_pk_bf16_f32 v2, v28, v29
	v_cvt_pk_bf16_f32 v3, v30, v31
	ds_write2_b64 v4, v[0:1], v[2:3] offset0:68 offset1:70
	v_cvt_pk_bf16_f32 v0, v32, v33
	v_cvt_pk_bf16_f32 v1, v34, v35
	v_cvt_pk_bf16_f32 v2, v36, v37
	v_cvt_pk_bf16_f32 v3, v38, v39
	ds_write2_b64 v85, v[0:1], v[2:3] offset0:8 offset1:10
	v_cvt_pk_bf16_f32 v0, v40, v41
	v_cvt_pk_bf16_f32 v1, v42, v43
	v_cvt_pk_bf16_f32 v2, v44, v45
	v_cvt_pk_bf16_f32 v3, v46, v47
	ds_write2_b64 v85, v[0:1], v[2:3] offset0:12 offset1:14
	v_cvt_pk_bf16_f32 v0, v48, v49
	v_cvt_pk_bf16_f32 v1, v50, v51
	v_cvt_pk_bf16_f32 v2, v52, v53
	v_cvt_pk_bf16_f32 v3, v54, v55
	s_ashr_i32 s19, s18, 31
	ds_write2_b64 v4, v[0:1], v[2:3] offset0:72 offset1:74
	v_cvt_pk_bf16_f32 v0, v56, v57
	v_cvt_pk_bf16_f32 v1, v58, v59
	v_cvt_pk_bf16_f32 v2, v60, v61
	v_cvt_pk_bf16_f32 v3, v62, v63
	s_lshl_b64 s[0:1], s[18:19], 15
	ds_write2_b64 v4, v[0:1], v[2:3] offset0:76 offset1:78
	v_add_u32_e32 v64, v95, v98
	s_lshl_b64 s[0:1], s[18:19], 6
	s_add_u32 s0, s92, s0
	s_addc_u32 s1, s93, s1
	s_mov_b64 s[22:23], 0
	s_waitcnt vmcnt(0)
	ds_write_b128 v99, v[86:89]
	ds_write_b128 v100, v[90:93]
	ds_write_b128 v101, v[136:139]
	ds_write_b128 v102, v[140:143]
	ds_write_b128 v103, v[248:251]
	ds_write_b128 v104, v[252:255]
	ds_write_b128 v105, v[120:123]
	ds_write_b128 v106, v[126:129]
	s_waitcnt lgkmcnt(0)
	s_barrier
	ds_read_b128 v[16:19], v64 offset:8704
	ds_read_b128 v[20:23], v107 offset:43520
	ds_read_b128 v[0:3], v64
	ds_read_b128 v[86:89], v64 offset:32
	ds_read_b128 v[4:7], v107 offset:34816
	ds_read_b128 v[90:93], v107 offset:34848
	s_waitcnt lgkmcnt(1)
	v_mfma_f32_32x32x16_bf16 v[32:47], v[0:3], v[4:7], 0
	ds_read_b128 v[110:113], v64 offset:8736
	ds_read_b128 v[120:123], v107 offset:43552
	v_mfma_f32_32x32x16_bf16 v[48:63], v[0:3], v[20:23], 0
	v_mfma_f32_32x32x16_bf16 v[0:15], v[16:19], v[4:7], 0
	v_mfma_f32_32x32x16_bf16 v[16:31], v[16:19], v[20:23], 0
	s_waitcnt lgkmcnt(2)
	v_mfma_f32_32x32x16_bf16 v[32:47], v[86:89], v[90:93], v[32:47]
	s_waitcnt lgkmcnt(0)
	v_mfma_f32_32x32x16_bf16 v[48:63], v[86:89], v[120:123], v[48:63]
	v_mfma_f32_32x32x16_bf16 v[0:15], v[110:113], v[90:93], v[0:15]
	v_mfma_f32_32x32x16_bf16 v[16:31], v[110:113], v[120:123], v[16:31]
	ds_read_b128 v[86:89], v64 offset:64
	ds_read_b128 v[90:93], v64 offset:8768
	ds_read_b128 v[110:113], v107 offset:34880
	ds_read_b128 v[120:123], v107 offset:43584
	s_waitcnt lgkmcnt(1)
	v_mfma_f32_32x32x16_bf16 v[32:47], v[86:89], v[110:113], v[32:47]
	s_waitcnt lgkmcnt(0)
	v_mfma_f32_32x32x16_bf16 v[48:63], v[86:89], v[120:123], v[48:63]
	v_mfma_f32_32x32x16_bf16 v[0:15], v[90:93], v[110:113], v[0:15]
	v_mfma_f32_32x32x16_bf16 v[16:31], v[90:93], v[120:123], v[16:31]
	ds_read_b128 v[86:89], v64 offset:96
	ds_read_b128 v[90:93], v64 offset:8800
	ds_read_b128 v[110:113], v107 offset:34912
	ds_read_b128 v[120:123], v107 offset:43616
	s_waitcnt lgkmcnt(1)
	v_mfma_f32_32x32x16_bf16 v[32:47], v[86:89], v[110:113], v[32:47]
	s_waitcnt lgkmcnt(0)
	v_mfma_f32_32x32x16_bf16 v[48:63], v[86:89], v[120:123], v[48:63]
	v_mfma_f32_32x32x16_bf16 v[0:15], v[90:93], v[110:113], v[0:15]
	v_mfma_f32_32x32x16_bf16 v[16:31], v[90:93], v[120:123], v[16:31]
	ds_read_b128 v[86:89], v64 offset:128
	ds_read_b128 v[90:93], v64 offset:8832
	ds_read_b128 v[110:113], v107 offset:34944
	ds_read_b128 v[120:123], v107 offset:43648
	s_waitcnt lgkmcnt(1)
	v_mfma_f32_32x32x16_bf16 v[32:47], v[86:89], v[110:113], v[32:47]
	s_waitcnt lgkmcnt(0)
	v_mfma_f32_32x32x16_bf16 v[48:63], v[86:89], v[120:123], v[48:63]
	v_mfma_f32_32x32x16_bf16 v[0:15], v[90:93], v[110:113], v[0:15]
	v_mfma_f32_32x32x16_bf16 v[16:31], v[90:93], v[120:123], v[16:31]
	ds_read_b128 v[86:89], v64 offset:160
	ds_read_b128 v[90:93], v64 offset:8864
	ds_read_b128 v[110:113], v107 offset:34976
	ds_read_b128 v[120:123], v107 offset:43680
	s_waitcnt lgkmcnt(1)
	v_mfma_f32_32x32x16_bf16 v[32:47], v[86:89], v[110:113], v[32:47]
	s_waitcnt lgkmcnt(0)
	v_mfma_f32_32x32x16_bf16 v[48:63], v[86:89], v[120:123], v[48:63]
	v_mfma_f32_32x32x16_bf16 v[0:15], v[90:93], v[110:113], v[0:15]
	v_mfma_f32_32x32x16_bf16 v[16:31], v[90:93], v[120:123], v[16:31]
	ds_read_b128 v[86:89], v64 offset:192
	ds_read_b128 v[90:93], v64 offset:8896
	ds_read_b128 v[110:113], v107 offset:35008
	ds_read_b128 v[120:123], v107 offset:43712
	s_waitcnt lgkmcnt(1)
	v_mfma_f32_32x32x16_bf16 v[32:47], v[86:89], v[110:113], v[32:47]
	s_waitcnt lgkmcnt(0)
	v_mfma_f32_32x32x16_bf16 v[48:63], v[86:89], v[120:123], v[48:63]
	v_mfma_f32_32x32x16_bf16 v[0:15], v[90:93], v[110:113], v[0:15]
	v_mfma_f32_32x32x16_bf16 v[16:31], v[90:93], v[120:123], v[16:31]
	ds_read_b128 v[86:89], v64 offset:224
	ds_read_b128 v[90:93], v64 offset:8928
	ds_read_b128 v[110:113], v107 offset:35040
	ds_read_b128 v[120:123], v107 offset:43744
	s_waitcnt lgkmcnt(0)
	s_barrier
; DI int crow(int r, int h) { return (r & 3) + 8 * (r >> 2) + 4 * h; }
; DI float fmax_fast(float a, float b) { float r; asm("v_max_f32 %0, %1, %2" : "=v"(r) : "v"(a), "v"(b)); return r; }
; __device__ void phase_peerq(const Params& p, int bid, int nb, char* lds, const TileMap& tm) {
;     ...
;     }
;     __syncthreads();
; #pragma unroll
;     for (int i = 0; i < 2; ++i)
; #pragma unroll
;       for (int j = 0; j < 2; ++j)
; #pragma unroll
;         for (int r = 0; r < 16; ++r)
;           scs[(64 * wm + 32 * i + crow(r, h)) * SC_LD + 64 * wn + 32 * j + l31] = acc[i][j][r];
;     __syncthreads();
;     {
;       const int row = tid >> 1, half = tid & 1;
;       float* rp = scs + row * SC_LD + half;
;       const size_t ob = ((size_t)(m0 + row) * 16 + hp) * 16;
;       float gm[8];
; #pragma unroll
;       for (int g = 0; g < 8; ++g) {
;         float m = rp[16 * g];
; #pragma unroll
;         for (int j = 1; j < 8; ++j) m = fmax_fast(m, rp[16 * g + 2 * j]);
;         gm[g] = m;
;       }
	v_mfma_f32_32x32x16_bf16 v[32:47], v[86:89], v[110:113], v[32:47]
	v_mfma_f32_32x32x16_bf16 v[48:63], v[86:89], v[120:123], v[48:63]
	s_nop 11
	ds_write2_b32 v84, v32, v48 offset1:32
	ds_write2_b32 v84, v33, v49 offset0:130 offset1:162
	v_mfma_f32_32x32x16_bf16 v[0:15], v[90:93], v[110:113], v[0:15]
	v_add_u32_e32 v32, 0x400, v84
	ds_write2_b32 v32, v34, v50 offset0:4 offset1:36
	ds_write2_b32 v32, v35, v51 offset0:134 offset1:166
	v_add_u32_e32 v32, 0x1000, v84
	ds_write2_b32 v32, v36, v52 offset0:16 offset1:48
	ds_write2_b32 v32, v37, v53 offset0:146 offset1:178
	v_add_u32_e32 v32, 0x1400, v84
	ds_write2_b32 v32, v38, v54 offset0:20 offset1:52
	ds_write2_b32 v32, v39, v55 offset0:150 offset1:182
	v_add_u32_e32 v32, 0x2000, v84
	v_mfma_f32_32x32x16_bf16 v[16:31], v[90:93], v[120:123], v[16:31]
	ds_write2_b32 v32, v40, v56 offset0:32 offset1:64
	ds_write2_b32 v32, v41, v57 offset0:162 offset1:194
	v_add_u32_e32 v32, 0x2400, v84
	ds_write2_b32 v32, v42, v58 offset0:36 offset1:68
	ds_write2_b32 v32, v43, v59 offset0:166 offset1:198
	v_add_u32_e32 v32, 0x3000, v84
	ds_write2_b32 v32, v44, v60 offset0:48 offset1:80
	ds_write2_b32 v32, v45, v61 offset0:178 offset1:210
	v_add_u32_e32 v32, 0x3400, v84
	ds_write2_b32 v32, v46, v62 offset0:52 offset1:84
	ds_write2_b32 v32, v47, v63 offset0:182 offset1:214
	v_add_u32_e32 v32, 0x4000, v84
	ds_write2_b32 v32, v0, v16 offset0:64 offset1:96
	ds_write2_b32 v32, v1, v17 offset0:194 offset1:226
	v_add_u32_e32 v0, 0x4400, v84
	ds_write2_b32 v0, v2, v18 offset0:68 offset1:100
	ds_write2_b32 v0, v3, v19 offset0:198 offset1:230
	v_add_u32_e32 v0, 0x5000, v84
	ds_write2_b32 v0, v4, v20 offset0:80 offset1:112
	ds_write2_b32 v0, v5, v21 offset0:210 offset1:242
	v_add_u32_e32 v0, 0x5400, v84
	ds_write2_b32 v0, v6, v22 offset0:84 offset1:116
	ds_write2_b32 v0, v7, v23 offset0:214 offset1:246
	v_add_u32_e32 v0, 0x6000, v84
	ds_write2_b32 v0, v8, v24 offset0:96 offset1:128
	v_add_u32_e32 v0, 0x6200, v84
	ds_write2_b32 v0, v9, v25 offset0:98 offset1:130
	v_add_u32_e32 v0, 0x6400, v84
	ds_write2_b32 v0, v10, v26 offset0:100 offset1:132
	v_add_u32_e32 v0, 0x6600, v84
	ds_write2_b32 v0, v11, v27 offset0:102 offset1:134
	v_add_u32_e32 v0, 0x7000, v84
	ds_write2_b32 v0, v12, v28 offset0:112 offset1:144
	v_add_u32_e32 v0, 0x7200, v84
	ds_write2_b32 v0, v13, v29 offset0:114 offset1:146
	v_add_u32_e32 v0, 0x7400, v84
	ds_write2_b32 v0, v14, v30 offset0:116 offset1:148
	v_add_u32_e32 v0, 0x7600, v84
	ds_write2_b32 v0, v15, v31 offset0:118 offset1:150
	s_waitcnt lgkmcnt(0)
	s_barrier
	s_setprio 0
	ds_read2_b32 v[2:3], v97 offset1:2
	ds_read2_b32 v[4:5], v97 offset0:4 offset1:6
	ds_read2_b32 v[6:7], v97 offset0:8 offset1:10
	ds_read2_b32 v[8:9], v97 offset0:12 offset1:14
	s_waitcnt lgkmcnt(3)
	v_max_f32 v1, v2, v3
	s_waitcnt lgkmcnt(2)
	v_max_f32 v1, v1, v4
	ds_read2_b32 v[2:3], v97 offset0:16 offset1:18
	v_max_f32 v1, v1, v5
	v_add_u32_e32 v0, s3, v94
	s_waitcnt lgkmcnt(2)
	v_max_f32 v1, v1, v6
	s_nop 0
	v_max_f32 v1, v1, v7
	s_waitcnt lgkmcnt(1)
	v_max_f32 v1, v1, v8
	s_nop 0
	v_max_f32 v6, v1, v9
	s_waitcnt lgkmcnt(0)
	v_max_f32 v1, v2, v3
	ds_read2_b32 v[2:3], v97 offset0:20 offset1:22
	s_waitcnt lgkmcnt(0)
	v_max_f32 v1, v1, v2
	s_nop 0
	v_max_f32 v1, v1, v3
	ds_read2_b32 v[2:3], v97 offset0:24 offset1:26
	s_waitcnt lgkmcnt(0)
	v_max_f32 v1, v1, v2
	s_nop 0
	v_max_f32 v1, v1, v3
	ds_read2_b32 v[2:3], v97 offset0:28 offset1:30
	s_waitcnt lgkmcnt(0)
	v_max_f32 v1, v1, v2
	s_nop 0
	v_max_f32 v7, v1, v3
	ds_read2_b32 v[2:3], v97 offset0:32 offset1:34
	s_waitcnt lgkmcnt(0)
	v_max_f32 v1, v2, v3
	ds_read2_b32 v[2:3], v97 offset0:36 offset1:38
	s_waitcnt lgkmcnt(0)
	v_max_f32 v1, v1, v2
	s_nop 0
	v_max_f32 v1, v1, v3
	ds_read2_b32 v[2:3], v97 offset0:40 offset1:42
	s_waitcnt lgkmcnt(0)
	v_max_f32 v1, v1, v2
	s_nop 0
	v_max_f32 v1, v1, v3
	ds_read2_b32 v[2:3], v97 offset0:44 offset1:46
	s_waitcnt lgkmcnt(0)
	v_max_f32 v1, v1, v2
	s_nop 0
	v_max_f32 v8, v1, v3
	ds_read2_b32 v[2:3], v97 offset0:48 offset1:50
	s_waitcnt lgkmcnt(0)
	v_max_f32 v1, v2, v3
	ds_read2_b32 v[2:3], v97 offset0:52 offset1:54
	s_waitcnt lgkmcnt(0)
	v_max_f32 v1, v1, v2
	s_nop 0
	v_max_f32 v1, v1, v3
	ds_read2_b32 v[2:3], v97 offset0:56 offset1:58
	s_waitcnt lgkmcnt(0)
	v_max_f32 v1, v1, v2
	s_nop 0
	v_max_f32 v1, v1, v3
	ds_read2_b32 v[2:3], v97 offset0:60 offset1:62
	s_waitcnt lgkmcnt(0)
	v_max_f32 v1, v1, v2
	s_nop 0
	v_max_f32 v9, v1, v3
	ds_read2_b32 v[2:3], v97 offset0:64 offset1:66
	s_waitcnt lgkmcnt(0)
	v_max_f32 v1, v2, v3
	ds_read2_b32 v[2:3], v97 offset0:68 offset1:70
	s_waitcnt lgkmcnt(0)
	v_max_f32 v1, v1, v2
	s_nop 0
	v_max_f32 v1, v1, v3
	ds_read2_b32 v[2:3], v97 offset0:72 offset1:74
	s_waitcnt lgkmcnt(0)
	v_max_f32 v1, v1, v2
	s_nop 0
	v_max_f32 v1, v1, v3
	ds_read2_b32 v[2:3], v97 offset0:76 offset1:78
	s_waitcnt lgkmcnt(0)
	v_max_f32 v1, v1, v2
	s_nop 0
	v_max_f32 v10, v1, v3
	ds_read2_b32 v[2:3], v97 offset0:80 offset1:82
	s_waitcnt lgkmcnt(0)
	v_max_f32 v1, v2, v3
	ds_read2_b32 v[2:3], v97 offset0:84 offset1:86
	s_waitcnt lgkmcnt(0)
	v_max_f32 v1, v1, v2
	s_nop 0
	v_max_f32 v1, v1, v3
	ds_read2_b32 v[2:3], v97 offset0:88 offset1:90
	s_waitcnt lgkmcnt(0)
	v_max_f32 v1, v1, v2
	s_nop 0
	v_max_f32 v1, v1, v3
	ds_read2_b32 v[2:3], v97 offset0:92 offset1:94
	s_waitcnt lgkmcnt(0)
	v_max_f32 v1, v1, v2
	s_nop 0
	v_max_f32 v11, v1, v3
	ds_read2_b32 v[2:3], v97 offset0:96 offset1:98
	s_waitcnt lgkmcnt(0)
	v_max_f32 v1, v2, v3
	ds_read2_b32 v[2:3], v97 offset0:100 offset1:102
	s_waitcnt lgkmcnt(0)
	v_max_f32 v1, v1, v2
	s_nop 0
	v_max_f32 v1, v1, v3
	ds_read2_b32 v[2:3], v97 offset0:104 offset1:106
	s_waitcnt lgkmcnt(0)
	v_max_f32 v1, v1, v2
	s_nop 0
	v_max_f32 v1, v1, v3
	ds_read2_b32 v[2:3], v97 offset0:108 offset1:110
	s_waitcnt lgkmcnt(0)
	v_max_f32 v1, v1, v2
	s_nop 0
	v_max_f32 v12, v1, v3
	ds_read2_b32 v[2:3], v97 offset0:112 offset1:114
	s_waitcnt lgkmcnt(0)
	v_max_f32 v1, v2, v3
	ds_read2_b32 v[2:3], v97 offset0:116 offset1:118
	s_waitcnt lgkmcnt(0)
	v_max_f32 v1, v1, v2
	s_nop 0
	v_max_f32 v1, v1, v3
	ds_read2_b32 v[2:3], v97 offset0:120 offset1:122
	s_waitcnt lgkmcnt(0)
	v_max_f32 v1, v1, v2
	s_nop 0
	v_max_f32 v1, v1, v3
	ds_read2_b32 v[2:3], v97 offset0:124 offset1:126
	s_waitcnt lgkmcnt(0)
	v_max_f32 v1, v1, v2
	s_nop 0
	v_max_f32 v13, v1, v3
	v_ashrrev_i32_e32 v1, 31, v0
	v_lshlrev_b64 v[0:1], 10, v[0:1]
	v_lshl_add_u64 v[4:5], s[0:1], 0, v[0:1]
	s_branch .LBB0_455
